# row-sum MFMA ones fragment kept in VGPRs freed by the DMA staging (no per-tile v_mov_b64)
# baseline (speedup 1.0000x reference)
; #define ALAS __attribute__((address_space(3)))
; template <int NC> __device__ __forceinline__ int v_st(int k, int c) { const int kk = (k & ~0xC) | ((k & 4) << 1) | ((k & 8) >> 1); return ((kk >> 3) * NC + (c >> 5)) * 512 + ((kk & 7) * 32 + (c & 31)) * 2; }
; __device__ __forceinline__ int v_rd_base(int lane) { return ((lane & 3) << 3) | (((lane >> 2) & 3) << 6) | (((lane >> 4) & 1) << 5) | (((lane >> 5) & 1) << 8); }
; #define SLOADX(S, k0) do { sk##S = *reinterpret_cast<const bf16x8*>(Kh + (long)(k0) * LD + kgo); sva##S = *reinterpret_cast<const bf16x8*>(Vh + (long)(k0) * LD + vgo); \
;     if constexpr (DV == 128) svb##S = *reinterpret_cast<const bf16x8*>(Vh + (long)((k0) + 32) * LD + vgo); } while (0)
; template <int DV, bool NA>
; __device__ __forceinline__ void attn_core(const bf16_t* __restrict__ Qlane, const bf16_t* __restrict__ Kh, const bf16_t* __restrict__ Vh, const int NT,
;                                           ALAS char* lds, f32x16 (&o)[DV / 32], const NaCtx& na) {
;     ...
;   int tid_ = threadIdx.x; asm volatile("" : "+v"(tid_));
;   const int tid = tid_, wid = __builtin_amdgcn_readfirstlane(tid >> 6), lane = tid & 63, r32 = lane & 31, hi = lane >> 5;
;   ALAS char* V_lds = lds + L_V; ALAS char* K_lds = lds + L_K;
;   ALAS float* al_l = (ALAS float*)(lds + L_WS) + wid * 64;
;   float m_ref = 0.f;
;   f32x16 osum = f32x16{}, negm = f32x16{};
; #pragma unroll
;   for (int d = 0; d < NC; ++d) o[d] = f32x16{};
;   bf16x8 qr[4];
; #pragma unroll
;   for (int d0 = 0; d0 < 4; ++d0) qr[d0] = *reinterpret_cast<const bf16x8*>(Qlane + d0 * 16);
;   const bf16x8 ones = {0x3f80, 0x3f80, 0x3f80, 0x3f80, 0x3f80, 0x3f80, 0x3f80, 0x3f80};
;   const int kr_ = tid >> 3, kc8 = (tid & 7) * 8, kst = KSWZ(kr_, kc8 * 2);
;   const int vr_ = (DV == 128) ? (tid >> 4) : (tid >> 3), vc8 = (DV == 128) ? (tid & 15) * 8 : (tid & 7) * 8;
;   const int vst0 = v_st<NC>(vr_, vc8), vst1 = v_st<NC>((32 + vr_) & 63, vc8);
;   const int vb0 = (int)(uintptr_t)V_lds + v_rd_base(lane);
;   const int kgo = kr_ * LD + kc8, vgo = vr_ * LD + vc8;
;   bf16x8 sk0, sva0, svb0, sk1, sva1, svb1;
;     ...
;   SLOADX(0, 0); asm volatile("s_waitcnt vmcnt(0)" ::: "memory"); SWRITEX(0, 0); SLOADX(1, 64); SLOADX(0, 128); __syncthreads();
.LBB0_248:
	v_mov_b32_e32 v1, v228
	s_lshl_b64 s[50:51], s[36:37], 1
	v_ashrrev_i32_e32 v22, 3, v1
	v_lshlrev_b32_e32 v30, 3, v1
	v_and_b32_e32 v23, 56, v30
	v_ashrrev_i32_e32 v31, 4, v1
	v_mul_lo_u32 v2, v22, s0
	v_or_b32_e32 v2, v2, v23
	v_mul_lo_u32 v3, v31, s0
	s_add_u32 s34, s20, s50
	v_and_or_b32 v4, v30, s33, v3
	v_lshrrev_b32_e32 v5, 3, v1
	v_mul_lo_u32 v2, v5, s0
	v_bfe_u32 v5, v1, 4, 3
	v_and_b32_e32 v6, 7, v1
	v_xor_b32_e32 v5, v5, v6
	v_lshl_or_b32 v2, v5, 3, v2
	v_bfe_u32 v5, v1, 2, 2
	v_bfe_u32 v6, v1, 7, 1
	v_lshl_or_b32 v5, v6, 2, v5
	v_bfe_u32 v6, v1, 4, 1
	v_lshl_or_b32 v5, v6, 3, v5
	v_bfe_u32 v6, v1, 8, 1
	v_lshl_or_b32 v5, v6, 4, v5
	v_mul_lo_u32 v4, v5, s0
	v_bfe_u32 v5, v1, 5, 2
	v_lshl_or_b32 v4, v5, 5, v4
	v_and_b32_e32 v5, 3, v1
	v_lshl_or_b32 v4, v5, 3, v4
	v_ashrrev_i32_e32 v3, 31, v2
	s_addc_u32 s35, s21, s51
	v_lshlrev_b64 v[14:15], 1, v[2:3]
	v_lshl_add_u64 v[16:17], s[34:35], 0, v[14:15]
	v_ashrrev_i32_e32 v5, 31, v4
	s_mov_b32 s34, 0x30000
	v_lshlrev_b64 v[18:19], 1, v[4:5]
	v_add_co_u32_e32 v28, vcc, s34, v16
	v_lshl_add_u64 v[2:3], s[20:21], 0, v[18:19]
	v_lshl_add_u64 v[6:7], s[26:27], 0, v[18:19]
	v_lshl_add_u64 v[20:21], v[208:209], 0, s[50:51]
	v_addc_co_u32_e32 v29, vcc, 0, v17, vcc
	v_readfirstlane_b32 s98, v1
	s_nop 0
	s_lshr_b32 s98, s98, 6
	s_lshl_b32 s98, s98, 10
	s_add_u32 s100, s20, 0x800
	s_addc_u32 s101, s21, 0
	v_lshl_add_u64 v[2:3], s[100:101], 0, v[18:19]
	s_mov_b32 m0, s98
	s_nop 0
	global_load_lds_dwordx4 v[2:3], off
	s_add_i32 m0, s98, 0x2000
	s_nop 0
	global_load_lds_dwordx4 v[6:7], off
	s_movk_i32 s100, 0x400
	s_mov_b32 s101, 0
	v_lshl_add_u64 v[10:11], v[16:17], 0, s[100:101]
	s_add_i32 m0, s98, 0x8000
	s_nop 0
	global_load_lds_dwordx4 v[10:11], off
	global_load_dwordx4 v[160:163], v[20:21], off
	global_load_dwordx4 v[164:167], v[20:21], off offset:32
	global_load_dwordx4 v[168:171], v[20:21], off offset:64
	global_load_dwordx4 v[172:175], v[20:21], off offset:96
	v_lshlrev_b32_e32 v20, 4, v1
	v_lshlrev_b32_e32 v21, 1, v1
	v_lshlrev_b32_e32 v35, 7, v22
	v_lshlrev_b32_e32 v22, 1, v31
	v_lshrrev_b32_e32 v24, 1, v31
	v_and_b32_e32 v25, 3, v31
	s_waitcnt vmcnt(0)
	v_add_co_u32_e32 v16, vcc, s24, v16
	v_and_b32_e32 v37, 48, v20
	v_and_b32_e32 v38, 0xc0, v20
	v_and_b32_e32 v39, 32, v21
	v_lshlrev_b32_e32 v40, 1, v23
	v_and_b32_e32 v41, 8, v22
	v_and_or_b32 v42, v24, 4, v25
	v_lshl_add_u64 v[20:21], s[38:39], 0, v[18:19]
	v_lshl_add_u64 v[22:23], s[40:41], 0, v[18:19]
	v_lshl_add_u64 v[24:25], s[42:43], 0, v[18:19]
	v_lshl_add_u64 v[26:27], s[44:45], 0, v[18:19]
	v_addc_co_u32_e32 v17, vcc, 0, v17, vcc
	s_mov_b32 s34, 0xfffff0
	v_and_b32_e32 v34, 0x70, v1
	v_and_or_b32 v17, v31, s34, v41
	v_and_or_b32 v21, v31, 48, v41
	v_bfe_u32 v36, v30, 5, 2
	v_bitop3_b32 v16, v40, v35, v34 bitop3:0xde
	v_lshrrev_b32_e32 v17, 1, v17
	v_lshrrev_b32_e32 v21, 1, v21
	v_readfirstlane_b32 s22, v1
	v_lshlrev_b32_e32 v20, 6, v42
	v_add_u32_e32 v217, 0, v16
	v_or_b32_e32 v16, v17, v36
	v_or_b32_e32 v17, v21, v36
	v_and_b32_e32 v32, 31, v1
	v_and_b32_e32 v33, 63, v1
	v_lshrrev_b32_e32 v1, 1, v1
	s_and_b32 s22, s22, 0x3fffffc0
	v_lshl_or_b32 v17, v17, 9, v20
	s_movk_i32 s34, 0x2000
	s_lshl_b32 s22, s22, 2
	v_bitop3_b32 v17, v17, s34, v37 bitop3:0x36
	v_and_b32_e32 v220, 16, v1
	s_movk_i32 s34, 0x70
	s_add_i32 s22, s22, 0
	v_add_u32_e32 v219, 0, v17
	v_and_b32_e32 v1, 0x70, v30
	v_bitop3_b32 v17, v30, v220, s34 bitop3:0x6c
	s_movk_i32 s34, 0x60
	v_lshlrev_b32_e32 v16, 9, v16
	v_bitop3_b32 v22, v220, v1, s34 bitop3:0x36
	s_add_u32 s34, s46, s50
	v_or3_b32 v16, v16, v20, v37
	s_addc_u32 s35, s47, s51
	v_add_u32_e32 v218, 0, v16
	v_lshl_add_u32 v16, v32, 7, 0
	v_bitop3_b32 v20, v220, v1, 32 bitop3:0x36
	v_bitop3_b32 v21, v220, v1, 64 bitop3:0x36
	v_and_or_b32 v1, v30, s3, v39
	v_lshl_add_u64 v[212:213], s[34:35], 0, v[14:15]
	v_mov_b32_e32 v14, v0
	v_mov_b32_e32 v15, v0
	v_cmp_gt_u32_e64 s[36:37], 32, v33
	v_lshl_add_u32 v221, v32, 2, s22
	v_add3_u32 v222, v38, 0, v1
	v_lshl_add_u64 v[210:211], s[46:47], 0, v[18:19]
	v_mov_b32_e32 v1, v0
	v_mov_b32_e32 v2, v0
	v_mov_b32_e32 v3, v0
	v_mov_b32_e32 v4, v0
	v_mov_b32_e32 v5, v0
	v_mov_b32_e32 v6, v0
	v_mov_b32_e32 v7, v0
	v_mov_b32_e32 v8, v0
	v_mov_b32_e32 v9, v0
	v_mov_b32_e32 v10, v0
	v_mov_b32_e32 v11, v0
	v_mov_b32_e32 v12, v0
	v_mov_b32_e32 v13, v0
	v_mov_b32_e32 v224, 0
	v_add_u32_e32 v225, v16, v17
	v_add_u32_e32 v226, v16, v20
	v_add_u32_e32 v227, v16, v21
	v_add_u32_e32 v236, v16, v22
	v_mov_b64_e32 v[78:79], v[14:15]
	v_mov_b64_e32 v[62:63], v[14:15]
	v_mov_b64_e32 v[46:47], v[14:15]
	v_mov_b64_e32 v[30:31], v[14:15]
	v_mov_b64_e32 v[94:95], v[14:15]
	v_add_u32_e32 v223, 0x4000, v222
	s_mov_b32 s59, -2
	v_mov_b64_e32 v[76:77], v[12:13]
	v_mov_b64_e32 v[74:75], v[10:11]
	v_mov_b64_e32 v[72:73], v[8:9]
	v_mov_b64_e32 v[70:71], v[6:7]
	v_mov_b64_e32 v[68:69], v[4:5]
	v_mov_b64_e32 v[66:67], v[2:3]
	v_mov_b64_e32 v[64:65], v[0:1]
	v_mov_b64_e32 v[60:61], v[12:13]
	v_mov_b64_e32 v[58:59], v[10:11]
	v_mov_b64_e32 v[56:57], v[8:9]
	v_mov_b64_e32 v[54:55], v[6:7]
	v_mov_b64_e32 v[52:53], v[4:5]
	v_mov_b64_e32 v[50:51], v[2:3]
	v_mov_b64_e32 v[48:49], v[0:1]
	v_mov_b64_e32 v[44:45], v[12:13]
	v_mov_b64_e32 v[42:43], v[10:11]
	v_mov_b64_e32 v[40:41], v[8:9]
	v_mov_b64_e32 v[38:39], v[6:7]
	v_mov_b64_e32 v[36:37], v[4:5]
	v_mov_b64_e32 v[34:35], v[2:3]
	v_mov_b64_e32 v[32:33], v[0:1]
	v_mov_b64_e32 v[28:29], v[12:13]
	v_mov_b64_e32 v[26:27], v[10:11]
	v_mov_b64_e32 v[24:25], v[8:9]
	v_mov_b64_e32 v[22:23], v[6:7]
	v_mov_b64_e32 v[20:21], v[4:5]
	v_mov_b64_e32 v[18:19], v[2:3]
	v_mov_b64_e32 v[16:17], v[0:1]
	v_mov_b64_e32 v[92:93], v[12:13]
	v_mov_b64_e32 v[90:91], v[10:11]
	v_mov_b64_e32 v[88:89], v[8:9]
	v_mov_b64_e32 v[86:87], v[6:7]
	v_mov_b64_e32 v[84:85], v[4:5]
	v_mov_b64_e32 v[82:83], v[2:3]
	v_mov_b64_e32 v[80:81], v[0:1]
	v_mov_b32_e32 v112, 0
	v_mov_b32_e32 v113, v224
	v_mov_b32_e32 v114, v224
	v_mov_b32_e32 v115, v224
	v_mov_b32_e32 v116, v224
	v_mov_b32_e32 v117, v224
	v_mov_b32_e32 v118, v224
	v_mov_b32_e32 v119, v224
	v_mov_b32_e32 v120, v224
	v_mov_b32_e32 v121, v224
	v_mov_b32_e32 v122, v224
	v_mov_b32_e32 v123, v224
	v_mov_b32_e32 v124, v224
	v_mov_b32_e32 v125, v224
	v_mov_b32_e32 v126, v224
	v_mov_b32_e32 v127, v224
	v_mov_b64_e32 v[176:177], s[8:9]
	v_mov_b64_e32 v[178:179], s[10:11]
	s_waitcnt lgkmcnt(0)
	s_barrier

; #define SBAR() __builtin_amdgcn_sched_barrier(0)
; #define EXP8(P, BASE) do { _Pragma("unroll") for (int r = 0; r < 8; ++r) P[BASE + r] = __builtin_amdgcn_exp2f(P[BASE + r]); } while (0)
; #define LGKM(n) asm volatile("s_waitcnt lgkmcnt(" #n ")" ::: "memory")
; template <int NC> __device__ __forceinline__ void v_mma_k(f32x16* o, f32x16& osum, const s16x4 (&L)[8], bf16x8 pa, bf16x8 ones) {
;     ...
;   osum = __builtin_amdgcn_mfma_f32_32x32x16_bf16(pa, ones, osum, 0, 0, 0);
;   o[0] = __builtin_amdgcn_mfma_f32_32x32x16_bf16(pa, PK(L[0], L[1]), o[0], 0, 0, 0);
;   o[1] = __builtin_amdgcn_mfma_f32_32x32x16_bf16(pa, PK(L[2], L[3]), o[1], 0, 0, 0);
;   if constexpr (NC == 4) { o[2] = __builtin_amdgcn_mfma_f32_32x32x16_bf16(pa, PK(L[4], L[5]), o[2], 0, 0, 0); o[3] = __builtin_amdgcn_mfma_f32_32x32x16_bf16(pa, PK(L[6], L[7]), o[3], 0, 0, 0); }
;     ...
; }
; template <int DV, bool NA>
; __device__ __forceinline__ void attn_core(const bf16_t* __restrict__ Qlane, const bf16_t* __restrict__ Kh, const bf16_t* __restrict__ Vh, const int NT,
;                                           ALAS char* lds, f32x16 (&o)[DV / 32], const NaCtx& na) {
;     ...
;       const int vb = vb0 + b * SHM_V;
;       s16x4 LA[8], LB[8]; bf16x8 pa;
;     ...
;       v_issue_k<NC, 0>(LA, vb);
;       EXP8(p0, 0); PK4(p0, 0, pa); SBAR();
;       v_issue_k<NC, 1>(LB, vb); if constexpr (NC == 4) LGKM(8); else LGKM(4); SBAR(); v_mma_k<NC>(o, osum, LA, pa, ones); SBAR();
;       EXP8(p0, 8); PK4(p0, 8, pa); SBAR();
;       v_issue_k<NC, 2>(LA, vb); if constexpr (NC == 4) LGKM(8); else LGKM(4); SBAR(); v_mma_k<NC>(o, osum, LB, pa, ones); SBAR();
;       EXP8(p1, 0); PK4(p1, 0, pa); SBAR();
;       v_issue_k<NC, 3>(LB, vb); if constexpr (NC == 4) LGKM(8); else LGKM(4); SBAR(); v_mma_k<NC>(o, osum, LA, pa, ones); SBAR();
;       EXP8(p1, 8); PK4(p1, 8, pa); SBAR();
;       LGKM(0); SBAR(); v_mma_k<NC>(o, osum, LB, pa, ones);
.LBB0_253:
	ds_read_b64_tr_b16 v[2:3], v222 offset:0
	ds_read_b64_tr_b16 v[4:5], v222 offset:0x800
	ds_read_b64_tr_b16 v[6:7], v222 offset:0x200
	ds_read_b64_tr_b16 v[8:9], v222 offset:0xa00
	ds_read_b64_tr_b16 v[10:11], v222 offset:0x400
	v_exp_f32_e32 v1, v144
	v_exp_f32_e32 v14, v145
	v_exp_f32_e32 v15, v146
	v_exp_f32_e32 v145, v147
	v_exp_f32_e32 v146, v148
	v_exp_f32_e32 v147, v149
	v_exp_f32_e32 v148, v150
	v_exp_f32_e32 v149, v151
	ds_read_b64_tr_b16 v[12:13], v222 offset:0xc00
	ds_read_b64_tr_b16 v[200:201], v222 offset:0x600
	ds_read_b64_tr_b16 v[202:203], v222 offset:0xe00
	v_cvt_pk_bf16_f32 v144, v1, v14
	v_cvt_pk_bf16_f32 v145, v15, v145
	v_cvt_pk_bf16_f32 v146, v146, v147
	v_cvt_pk_bf16_f32 v147, v148, v149
	s_nop 0
	v_permlane32_swap_b32_e32 v144, v146
	v_permlane32_swap_b32_e32 v145, v147
	s_add_i32 s50, s59, 3
	ds_read_b64_tr_b16 v[148:149], v222 offset:0x1000
	ds_read_b64_tr_b16 v[150:151], v222 offset:0x1800
	ds_read_b64_tr_b16 v[238:239], v222 offset:0x1200
	ds_read_b64_tr_b16 v[240:241], v222 offset:0x1a00
	ds_read_b64_tr_b16 v[242:243], v222 offset:0x1400
	ds_read_b64_tr_b16 v[244:245], v222 offset:0x1c00
	ds_read_b64_tr_b16 v[246:247], v222 offset:0x1600
	ds_read_b64_tr_b16 v[248:249], v222 offset:0x1e00
	s_waitcnt lgkmcnt(8)
	v_mfma_f32_32x32x16_bf16 v[64:79], v[144:147], v[2:5], v[64:79]
	v_mfma_f32_32x32x16_bf16 v[48:63], v[144:147], v[6:9], v[48:63]
	v_mfma_f32_32x32x16_bf16 v[32:47], v[144:147], v[10:13], v[32:47]
	v_mfma_f32_32x32x16_bf16 v[16:31], v[144:147], v[200:203], v[16:31]
	v_exp_f32_e32 v1, v152
	v_exp_f32_e32 v2, v153
	v_exp_f32_e32 v3, v154
	v_exp_f32_e32 v4, v155
	v_exp_f32_e32 v5, v156
	v_exp_f32_e32 v6, v157
	v_exp_f32_e32 v7, v158
	v_exp_f32_e32 v8, v159
	v_cvt_pk_bf16_f32 v2, v1, v2
	v_cvt_pk_bf16_f32 v3, v3, v4
	v_cvt_pk_bf16_f32 v4, v5, v6
	v_cvt_pk_bf16_f32 v5, v7, v8
	s_nop 0
	v_permlane32_swap_b32_e32 v2, v4
	v_permlane32_swap_b32_e32 v3, v5
	ds_read_b64_tr_b16 v[6:7], v222 offset:0x2000
	ds_read_b64_tr_b16 v[8:9], v222 offset:0x2800
	ds_read_b64_tr_b16 v[10:11], v222 offset:0x2200
	ds_read_b64_tr_b16 v[12:13], v222 offset:0x2a00
	ds_read_b64_tr_b16 v[152:153], v222 offset:0x2400
	ds_read_b64_tr_b16 v[154:155], v222 offset:0x2c00
	ds_read_b64_tr_b16 v[156:157], v222 offset:0x2600
	ds_read_b64_tr_b16 v[158:159], v222 offset:0x2e00
	s_waitcnt lgkmcnt(8)
	v_mfma_f32_32x32x16_bf16 v[64:79], v[2:5], v[148:151], v[64:79]
	v_mfma_f32_32x32x16_bf16 v[48:63], v[2:5], v[238:241], v[48:63]
	v_mfma_f32_32x32x16_bf16 v[32:47], v[2:5], v[242:245], v[32:47]
	v_mfma_f32_32x32x16_bf16 v[16:31], v[2:5], v[246:249], v[16:31]
	v_exp_f32_e32 v1, v128
	v_exp_f32_e32 v14, v129
	v_exp_f32_e32 v15, v130
	v_exp_f32_e32 v148, v131
	v_exp_f32_e32 v149, v132
	v_exp_f32_e32 v150, v133
	v_mfma_f32_32x32x16_bf16 v[80:95], v[144:147], v[176:179], v[80:95]
	v_exp_f32_e32 v151, v134
	v_exp_f32_e32 v135, v135
	v_cvt_pk_bf16_f32 v132, v1, v14
	v_cvt_pk_bf16_f32 v133, v15, v148
	v_cvt_pk_bf16_f32 v134, v149, v150
	v_cvt_pk_bf16_f32 v135, v151, v135
	s_nop 0
	v_permlane32_swap_b32_e32 v132, v134
	v_permlane32_swap_b32_e32 v133, v135
	ds_read_b64_tr_b16 v[144:145], v222 offset:0x3000
	ds_read_b64_tr_b16 v[146:147], v222 offset:0x3800
	ds_read_b64_tr_b16 v[148:149], v222 offset:0x3200
	ds_read_b64_tr_b16 v[150:151], v222 offset:0x3a00
	ds_read_b64_tr_b16 v[200:201], v222 offset:0x3400
	ds_read_b64_tr_b16 v[202:203], v222 offset:0x3c00
	ds_read_b64_tr_b16 v[238:239], v222 offset:0x3600
	ds_read_b64_tr_b16 v[240:241], v222 offset:0x3e00
	s_waitcnt lgkmcnt(8)
	v_mfma_f32_32x32x16_bf16 v[64:79], v[132:135], v[6:9], v[64:79]
	v_mfma_f32_32x32x16_bf16 v[48:63], v[132:135], v[10:13], v[48:63]
	v_mfma_f32_32x32x16_bf16 v[32:47], v[132:135], v[152:155], v[32:47]
	v_mfma_f32_32x32x16_bf16 v[16:31], v[132:135], v[156:159], v[16:31]
	v_mfma_f32_32x32x16_bf16 v[80:95], v[2:5], v[176:179], v[80:95]
	v_exp_f32_e32 v1, v136
	v_exp_f32_e32 v6, v137
	v_exp_f32_e32 v7, v138
	v_exp_f32_e32 v8, v139
	v_exp_f32_e32 v9, v140
	v_exp_f32_e32 v4, v141
	v_exp_f32_e32 v5, v142
	v_mfma_f32_32x32x16_bf16 v[80:95], v[132:135], v[176:179], v[80:95]
	v_exp_f32_e32 v10, v143
	v_cvt_pk_bf16_f32 v2, v1, v6
	v_cvt_pk_bf16_f32 v3, v7, v8
	v_cvt_pk_bf16_f32 v4, v9, v4
	v_cvt_pk_bf16_f32 v5, v5, v10
	s_nop 0
	v_permlane32_swap_b32_e32 v2, v4
	v_permlane32_swap_b32_e32 v3, v5
	s_waitcnt lgkmcnt(0)
	s_nop 1
	v_mfma_f32_32x32x16_bf16 v[80:95], v[2:5], v[176:179], v[80:95]
	s_waitcnt lgkmcnt(0)
	s_waitcnt vmcnt(0)
	s_barrier
	s_cmp_gt_u32 s50, 62
	v_mfma_f32_32x32x16_bf16 v[64:79], v[2:5], v[144:147], v[64:79]
	v_mfma_f32_32x32x16_bf16 v[48:63], v[2:5], v[148:151], v[48:63]
	v_mfma_f32_32x32x16_bf16 v[32:47], v[2:5], v[200:203], v[32:47]
	v_mfma_f32_32x32x16_bf16 v[16:31], v[2:5], v[238:241], v[16:31]
	ds_read_b128 v[156:159], v225 offset:40960
	ds_read_b128 v[200:203], v225 offset:45056
	ds_read_b128 v[152:155], v226 offset:40960
	ds_read_b128 v[148:151], v226 offset:45056
	ds_read_b128 v[144:147], v227 offset:40960
	ds_read_b128 v[10:13], v227 offset:45056
	ds_read_b128 v[2:5], v236 offset:40960
	ds_read_b128 v[6:9], v236 offset:45056
	s_cbranch_scc1 .LBB0_256
	v_lshl_add_u64 v[14:15], v[212:213], 0, s[6:7]
	v_add_co_u32_e32 v14, vcc, 0x1f860400, v14
	s_add_i32 m0, s98, 0x8000
	s_nop 0
	v_addc_co_u32_e32 v15, vcc, 0, v15, vcc
	global_load_lds_dwordx4 v[14:15], off
	v_lshl_add_u64 v[14:15], v[210:211], 0, s[6:7]
	v_add_co_u32_e32 v128, vcc, 0x1f860800, v14
	s_mov_b32 m0, s98
	s_nop 0
	v_addc_co_u32_e32 v129, vcc, 0, v15, vcc
	v_add_co_u32_e32 v14, vcc, 0x1f878800, v14
	global_load_lds_dwordx4 v[128:129], off
	s_add_i32 m0, s98, 0x2000
	s_nop 0
	v_addc_co_u32_e32 v15, vcc, 0, v15, vcc
	global_load_lds_dwordx4 v[14:15], off

; #define SBAR() __builtin_amdgcn_sched_barrier(0)
; #define EXP8(P, BASE) do { _Pragma("unroll") for (int r = 0; r < 8; ++r) P[BASE + r] = __builtin_amdgcn_exp2f(P[BASE + r]); } while (0)
; #define LGKM(n) asm volatile("s_waitcnt lgkmcnt(" #n ")" ::: "memory")
; template <int NC> __device__ __forceinline__ void v_mma_k(f32x16* o, f32x16& osum, const s16x4 (&L)[8], bf16x8 pa, bf16x8 ones) {
;     ...
;   osum = __builtin_amdgcn_mfma_f32_32x32x16_bf16(pa, ones, osum, 0, 0, 0);
;   o[0] = __builtin_amdgcn_mfma_f32_32x32x16_bf16(pa, PK(L[0], L[1]), o[0], 0, 0, 0);
;   o[1] = __builtin_amdgcn_mfma_f32_32x32x16_bf16(pa, PK(L[2], L[3]), o[1], 0, 0, 0);
;   if constexpr (NC == 4) { o[2] = __builtin_amdgcn_mfma_f32_32x32x16_bf16(pa, PK(L[4], L[5]), o[2], 0, 0, 0); o[3] = __builtin_amdgcn_mfma_f32_32x32x16_bf16(pa, PK(L[6], L[7]), o[3], 0, 0, 0); }
;     ...
; }
; template <int DV, bool NA>
; __device__ __forceinline__ void attn_core(const bf16_t* __restrict__ Qlane, const bf16_t* __restrict__ Kh, const bf16_t* __restrict__ Vh, const int NT,
;                                           ALAS char* lds, f32x16 (&o)[DV / 32], const NaCtx& na) {
;     ...
;       const int vb = vb0 + b * SHM_V;
;       s16x4 LA[8], LB[8]; bf16x8 pa;
;     ...
;       v_issue_k<NC, 0>(LA, vb);
;       EXP8(p0, 0); PK4(p0, 0, pa); SBAR();
;       v_issue_k<NC, 1>(LB, vb); if constexpr (NC == 4) LGKM(8); else LGKM(4); SBAR(); v_mma_k<NC>(o, osum, LA, pa, ones); SBAR();
;       EXP8(p0, 8); PK4(p0, 8, pa); SBAR();
;       v_issue_k<NC, 2>(LA, vb); if constexpr (NC == 4) LGKM(8); else LGKM(4); SBAR(); v_mma_k<NC>(o, osum, LB, pa, ones); SBAR();
;       EXP8(p1, 0); PK4(p1, 0, pa); SBAR();
;       v_issue_k<NC, 3>(LB, vb); if constexpr (NC == 4) LGKM(8); else LGKM(4); SBAR(); v_mma_k<NC>(o, osum, LA, pa, ones); SBAR();
;       EXP8(p1, 8); PK4(p1, 8, pa); SBAR();
;       LGKM(0); SBAR(); v_mma_k<NC>(o, osum, LB, pa, ones);
.LBB0_257:
	ds_read_b64_tr_b16 v[2:3], v223 offset:0
	ds_read_b64_tr_b16 v[4:5], v223 offset:0x800
	ds_read_b64_tr_b16 v[6:7], v223 offset:0x200
	ds_read_b64_tr_b16 v[8:9], v223 offset:0xa00
	ds_read_b64_tr_b16 v[10:11], v223 offset:0x400
	ds_read_b64_tr_b16 v[12:13], v223 offset:0xc00
	v_exp_f32_e32 v1, v128
	v_exp_f32_e32 v14, v129
	v_exp_f32_e32 v15, v130
	v_exp_f32_e32 v129, v131
	v_exp_f32_e32 v130, v132
	v_exp_f32_e32 v131, v133
	v_exp_f32_e32 v132, v134
	v_exp_f32_e32 v133, v135
	ds_read_b64_tr_b16 v[144:145], v223 offset:0x600
	ds_read_b64_tr_b16 v[146:147], v223 offset:0xe00
	v_cvt_pk_bf16_f32 v128, v1, v14
	v_cvt_pk_bf16_f32 v129, v15, v129
	v_cvt_pk_bf16_f32 v130, v130, v131
	v_cvt_pk_bf16_f32 v131, v132, v133
	s_nop 0
	v_permlane32_swap_b32_e32 v128, v130
	v_permlane32_swap_b32_e32 v129, v131
	ds_read_b64_tr_b16 v[132:133], v223 offset:0x1000
	ds_read_b64_tr_b16 v[134:135], v223 offset:0x1800
	ds_read_b64_tr_b16 v[148:149], v223 offset:0x1200
	ds_read_b64_tr_b16 v[150:151], v223 offset:0x1a00
	ds_read_b64_tr_b16 v[152:153], v223 offset:0x1400
	ds_read_b64_tr_b16 v[154:155], v223 offset:0x1c00
	ds_read_b64_tr_b16 v[156:157], v223 offset:0x1600
	ds_read_b64_tr_b16 v[158:159], v223 offset:0x1e00
	s_waitcnt lgkmcnt(8)
	v_mfma_f32_32x32x16_bf16 v[64:79], v[128:131], v[2:5], v[64:79]
	v_mfma_f32_32x32x16_bf16 v[48:63], v[128:131], v[6:9], v[48:63]
	v_mfma_f32_32x32x16_bf16 v[32:47], v[128:131], v[10:13], v[32:47]
	v_mfma_f32_32x32x16_bf16 v[16:31], v[128:131], v[144:147], v[16:31]
	v_exp_f32_e32 v1, v136
	v_exp_f32_e32 v2, v137
	v_exp_f32_e32 v3, v138
	v_exp_f32_e32 v4, v139
	v_exp_f32_e32 v5, v140
	v_exp_f32_e32 v6, v141
	v_exp_f32_e32 v7, v142
	v_exp_f32_e32 v8, v143
	v_cvt_pk_bf16_f32 v2, v1, v2
	v_cvt_pk_bf16_f32 v3, v3, v4
	v_cvt_pk_bf16_f32 v4, v5, v6
	v_cvt_pk_bf16_f32 v5, v7, v8
	s_nop 0
	v_permlane32_swap_b32_e32 v2, v4
	v_permlane32_swap_b32_e32 v3, v5
	ds_read_b64_tr_b16 v[6:7], v223 offset:0x2000
	ds_read_b64_tr_b16 v[8:9], v223 offset:0x2800
	ds_read_b64_tr_b16 v[10:11], v223 offset:0x2200
	ds_read_b64_tr_b16 v[12:13], v223 offset:0x2a00
	ds_read_b64_tr_b16 v[136:137], v223 offset:0x2400
	ds_read_b64_tr_b16 v[138:139], v223 offset:0x2c00
	ds_read_b64_tr_b16 v[140:141], v223 offset:0x2600
	ds_read_b64_tr_b16 v[142:143], v223 offset:0x2e00
	s_waitcnt lgkmcnt(8)
	v_mfma_f32_32x32x16_bf16 v[64:79], v[2:5], v[132:135], v[64:79]
	v_mfma_f32_32x32x16_bf16 v[48:63], v[2:5], v[148:151], v[48:63]
	v_mfma_f32_32x32x16_bf16 v[32:47], v[2:5], v[152:155], v[32:47]
	v_mfma_f32_32x32x16_bf16 v[16:31], v[2:5], v[156:159], v[16:31]
	v_exp_f32_e32 v1, v96
	v_exp_f32_e32 v14, v97
	v_exp_f32_e32 v15, v98
	v_exp_f32_e32 v132, v99
	v_exp_f32_e32 v133, v100
	v_exp_f32_e32 v134, v101
	v_mfma_f32_32x32x16_bf16 v[80:95], v[128:131], v[176:179], v[80:95]
	v_exp_f32_e32 v135, v102
	v_exp_f32_e32 v103, v103
	v_cvt_pk_bf16_f32 v100, v1, v14
	v_cvt_pk_bf16_f32 v101, v15, v132
	v_cvt_pk_bf16_f32 v102, v133, v134
	v_cvt_pk_bf16_f32 v103, v135, v103
	s_nop 0
	v_permlane32_swap_b32_e32 v100, v102
	v_permlane32_swap_b32_e32 v101, v103
	ds_read_b64_tr_b16 v[128:129], v223 offset:0x3000
	ds_read_b64_tr_b16 v[130:131], v223 offset:0x3800
	ds_read_b64_tr_b16 v[132:133], v223 offset:0x3200
	ds_read_b64_tr_b16 v[134:135], v223 offset:0x3a00
	ds_read_b64_tr_b16 v[144:145], v223 offset:0x3400
	ds_read_b64_tr_b16 v[146:147], v223 offset:0x3c00
	ds_read_b64_tr_b16 v[148:149], v223 offset:0x3600
	ds_read_b64_tr_b16 v[150:151], v223 offset:0x3e00
	s_waitcnt lgkmcnt(8)
	v_mfma_f32_32x32x16_bf16 v[64:79], v[100:103], v[6:9], v[64:79]
	v_mfma_f32_32x32x16_bf16 v[48:63], v[100:103], v[10:13], v[48:63]
	v_mfma_f32_32x32x16_bf16 v[32:47], v[100:103], v[136:139], v[32:47]
	v_mfma_f32_32x32x16_bf16 v[16:31], v[100:103], v[140:143], v[16:31]
	v_mfma_f32_32x32x16_bf16 v[80:95], v[2:5], v[176:179], v[80:95]
	v_exp_f32_e32 v1, v104
	v_exp_f32_e32 v6, v105
	v_exp_f32_e32 v7, v106
	v_exp_f32_e32 v8, v107
	v_exp_f32_e32 v9, v108
	v_exp_f32_e32 v4, v109
	v_exp_f32_e32 v5, v110
	v_mfma_f32_32x32x16_bf16 v[80:95], v[100:103], v[176:179], v[80:95]
	v_exp_f32_e32 v10, v111
	v_cvt_pk_bf16_f32 v2, v1, v6
	v_cvt_pk_bf16_f32 v3, v7, v8
	v_cvt_pk_bf16_f32 v4, v9, v4
	v_cvt_pk_bf16_f32 v5, v5, v10
	s_nop 0
	v_permlane32_swap_b32_e32 v2, v4
	v_permlane32_swap_b32_e32 v3, v5
	s_waitcnt lgkmcnt(0)
	s_nop 1
	v_mfma_f32_32x32x16_bf16 v[80:95], v[2:5], v[176:179], v[80:95]
	v_lshl_add_u64 v[210:211], v[210:211], 0, s[18:19]
	v_lshl_add_u64 v[212:213], v[212:213], 0, s[18:19]
	s_cmp_lt_u32 s58, 62
	s_waitcnt vmcnt(0)
	s_barrier
	v_mfma_f32_32x32x16_bf16 v[64:79], v[2:5], v[128:131], v[64:79]
	v_mfma_f32_32x32x16_bf16 v[48:63], v[2:5], v[132:135], v[48:63]
	v_mfma_f32_32x32x16_bf16 v[32:47], v[2:5], v[144:147], v[32:47]
	v_mfma_f32_32x32x16_bf16 v[16:31], v[2:5], v[148:151], v[16:31]
	s_cbranch_scc0 .LBB0_265
	s_mov_b32 s59, s58
	s_branch .LBB0_249

; #define ALAS __attribute__((address_space(3)))
; template <int NC> __device__ __forceinline__ int v_st(int k, int c) { const int kk = (k & ~0xC) | ((k & 4) << 1) | ((k & 8) >> 1); return ((kk >> 3) * NC + (c >> 5)) * 512 + ((kk & 7) * 32 + (c & 31)) * 2; }
; __device__ __forceinline__ int v_rd_base(int lane) { return ((lane & 3) << 3) | (((lane >> 2) & 3) << 6) | (((lane >> 4) & 1) << 5) | (((lane >> 5) & 1) << 8); }
; #define SLOADX(S, k0) do { sk##S = *reinterpret_cast<const bf16x8*>(Kh + (long)(k0) * LD + kgo); sva##S = *reinterpret_cast<const bf16x8*>(Vh + (long)(k0) * LD + vgo); \
;     if constexpr (DV == 128) svb##S = *reinterpret_cast<const bf16x8*>(Vh + (long)((k0) + 32) * LD + vgo); } while (0)
; template <int DV, bool NA>
; __device__ __forceinline__ void attn_core(const bf16_t* __restrict__ Qlane, const bf16_t* __restrict__ Kh, const bf16_t* __restrict__ Vh, const int NT,
;                                           ALAS char* lds, f32x16 (&o)[DV / 32], const NaCtx& na) {
;     ...
;   int tid_ = threadIdx.x; asm volatile("" : "+v"(tid_));
;   const int tid = tid_, wid = __builtin_amdgcn_readfirstlane(tid >> 6), lane = tid & 63, r32 = lane & 31, hi = lane >> 5;
;   ALAS char* V_lds = lds + L_V; ALAS char* K_lds = lds + L_K;
;   ALAS float* al_l = (ALAS float*)(lds + L_WS) + wid * 64;
;   float m_ref = 0.f;
;   f32x16 osum = f32x16{}, negm = f32x16{};
; #pragma unroll
;   for (int d = 0; d < NC; ++d) o[d] = f32x16{};
;   bf16x8 qr[4];
; #pragma unroll
;   for (int d0 = 0; d0 < 4; ++d0) qr[d0] = *reinterpret_cast<const bf16x8*>(Qlane + d0 * 16);
;   const bf16x8 ones = {0x3f80, 0x3f80, 0x3f80, 0x3f80, 0x3f80, 0x3f80, 0x3f80, 0x3f80};
;   const int kr_ = tid >> 3, kc8 = (tid & 7) * 8, kst = KSWZ(kr_, kc8 * 2);
;   const int vr_ = (DV == 128) ? (tid >> 4) : (tid >> 3), vc8 = (DV == 128) ? (tid & 15) * 8 : (tid & 7) * 8;
;   const int vst0 = v_st<NC>(vr_, vc8), vst1 = v_st<NC>((32 + vr_) & 63, vc8);
;   const int vb0 = (int)(uintptr_t)V_lds + v_rd_base(lane);
;   const int kgo = kr_ * LD + kc8, vgo = vr_ * LD + vc8;
;   bf16x8 sk0, sva0, svb0, sk1, sva1, svb1;
;     ...
;   SLOADX(0, 0); asm volatile("s_waitcnt vmcnt(0)" ::: "memory"); SWRITEX(0, 0); SLOADX(1, 64); SLOADX(0, 128); __syncthreads();
.LBB0_271:
	v_mov_b32_e32 v1, v228
	s_lshl_b64 s[50:51], s[36:37], 1
	v_ashrrev_i32_e32 v20, 3, v1
	v_lshlrev_b32_e32 v28, 3, v1
	v_and_b32_e32 v21, 56, v28
	v_ashrrev_i32_e32 v29, 4, v1
	v_mul_lo_u32 v2, v20, s0
	v_or_b32_e32 v2, v2, v21
	v_mul_lo_u32 v3, v29, s0
	s_add_u32 s34, s58, s50
	v_and_or_b32 v4, v28, s33, v3
	v_lshrrev_b32_e32 v5, 3, v1
	v_mul_lo_u32 v2, v5, s0
	v_bfe_u32 v5, v1, 4, 3
	v_and_b32_e32 v6, 7, v1
	v_xor_b32_e32 v5, v5, v6
	v_lshl_or_b32 v2, v5, 3, v2
	v_bfe_u32 v5, v1, 2, 2
	v_bfe_u32 v6, v1, 7, 1
	v_lshl_or_b32 v5, v6, 2, v5
	v_bfe_u32 v6, v1, 4, 1
	v_lshl_or_b32 v5, v6, 3, v5
	v_bfe_u32 v6, v1, 8, 1
	v_lshl_or_b32 v5, v6, 4, v5
	v_mul_lo_u32 v4, v5, s0
	v_bfe_u32 v5, v1, 5, 2
	v_lshl_or_b32 v4, v5, 5, v4
	v_and_b32_e32 v5, 3, v1
	v_lshl_or_b32 v4, v5, 3, v4
	v_ashrrev_i32_e32 v3, 31, v2
	s_addc_u32 s35, s59, s51
	v_lshlrev_b64 v[14:15], 1, v[2:3]
	v_lshl_add_u64 v[16:17], s[34:35], 0, v[14:15]
	v_ashrrev_i32_e32 v5, 31, v4
	s_mov_b32 s35, 0x30000
	v_lshlrev_b64 v[210:211], 1, v[4:5]
	v_add_co_u32_e32 v26, vcc, s35, v16
	v_lshl_add_u64 v[2:3], s[26:27], 0, v[210:211]
	v_lshl_add_u64 v[6:7], s[38:39], 0, v[210:211]
	v_lshl_add_u64 v[18:19], v[208:209], 0, s[50:51]
	v_addc_co_u32_e32 v27, vcc, 0, v17, vcc
	v_readfirstlane_b32 s98, v1
	s_nop 0
	s_lshr_b32 s98, s98, 6
	s_lshl_b32 s98, s98, 10
	s_mov_b32 m0, s98
	s_nop 0
	global_load_lds_dwordx4 v[2:3], off
	s_add_i32 m0, s98, 0x2000
	s_nop 0
	global_load_lds_dwordx4 v[6:7], off
	s_add_i32 m0, s98, 0x8000
	s_nop 0
	global_load_lds_dwordx4 v[16:17], off
	global_load_dwordx4 v[160:163], v[18:19], off
	global_load_dwordx4 v[164:167], v[18:19], off offset:32
	global_load_dwordx4 v[168:171], v[18:19], off offset:64
	global_load_dwordx4 v[172:175], v[18:19], off offset:96
	v_lshlrev_b32_e32 v18, 4, v1
	v_lshlrev_b32_e32 v19, 1, v1
	v_lshlrev_b32_e32 v33, 7, v20
	v_lshlrev_b32_e32 v20, 1, v29
	s_waitcnt vmcnt(0)
	v_add_co_u32_e32 v16, vcc, s24, v16
	v_and_b32_e32 v37, 48, v18
	v_and_b32_e32 v38, 0xc0, v18
	v_and_b32_e32 v39, 32, v19
	v_lshlrev_b32_e32 v40, 1, v21
	v_and_b32_e32 v41, 8, v20
	v_lshl_add_u64 v[18:19], s[40:41], 0, v[210:211]
	v_lshl_add_u64 v[20:21], s[42:43], 0, v[210:211]
	v_lshl_add_u64 v[22:23], s[44:45], 0, v[210:211]
	v_lshl_add_u64 v[24:25], s[46:47], 0, v[210:211]
	v_addc_co_u32_e32 v17, vcc, 0, v17, vcc
	v_readfirstlane_b32 s34, v1
	s_and_b32 s34, s34, 0x3fffffc0
	s_lshl_b32 s34, s34, 2
	s_add_i32 s60, s34, 0
	s_mov_b32 s34, 0xfffff0
	v_and_b32_e32 v32, 0x70, v1
	v_lshrrev_b32_e32 v34, 1, v29
	v_and_b32_e32 v36, 3, v29
	v_and_or_b32 v18, v29, s34, v41
	v_and_or_b32 v19, v29, 48, v41
	v_bfe_u32 v35, v28, 5, 2
	v_and_or_b32 v16, v34, 4, v36
	v_bitop3_b32 v17, v40, v33, v32 bitop3:0xde
	v_lshrrev_b32_e32 v18, 1, v18
	v_lshrrev_b32_e32 v19, 1, v19
	v_lshlrev_b32_e32 v16, 6, v16
	v_add_u32_e32 v217, 0, v17
	v_or_b32_e32 v17, v18, v35
	v_or_b32_e32 v18, v19, v35
	v_and_b32_e32 v30, 31, v1
	v_and_b32_e32 v31, 63, v1
	v_lshrrev_b32_e32 v1, 1, v1
	v_lshlrev_b32_e32 v17, 9, v17
	v_lshl_or_b32 v18, v18, 9, v16
	s_movk_i32 s34, 0x2000
	v_or3_b32 v16, v17, v16, v37
	v_bitop3_b32 v17, v18, s34, v37 bitop3:0x36
	v_and_b32_e32 v220, 16, v1
	s_movk_i32 s34, 0x70
	v_add_u32_e32 v219, 0, v17
	v_and_b32_e32 v1, 0x70, v28
	v_bitop3_b32 v17, v28, v220, s34 bitop3:0x6c
	s_movk_i32 s34, 0x60
	v_add_u32_e32 v218, 0, v16
	v_lshl_add_u32 v16, v30, 7, 0
	v_bitop3_b32 v18, v220, v1, 32 bitop3:0x36
	v_bitop3_b32 v19, v220, v1, 64 bitop3:0x36
	v_bitop3_b32 v20, v220, v1, s34 bitop3:0x36
	v_and_or_b32 v1, v28, s3, v39
	v_lshl_add_u64 v[212:213], s[50:51], 0, v[14:15]
	v_mov_b32_e32 v14, v0
	v_mov_b32_e32 v15, v0
	v_cmp_gt_u32_e64 s[36:37], 32, v31
	v_lshl_add_u32 v221, v30, 2, s60
	v_add3_u32 v222, v38, 0, v1
	v_mov_b32_e32 v1, v0
	v_mov_b32_e32 v2, v0
	v_mov_b32_e32 v3, v0
	v_mov_b32_e32 v4, v0
	v_mov_b32_e32 v5, v0
	v_mov_b32_e32 v6, v0
	v_mov_b32_e32 v7, v0
	v_mov_b32_e32 v8, v0
	v_mov_b32_e32 v9, v0
	v_mov_b32_e32 v10, v0
	v_mov_b32_e32 v11, v0
	v_mov_b32_e32 v12, v0
	v_mov_b32_e32 v13, v0
	v_mov_b32_e32 v224, 0
	v_add_u32_e32 v225, v16, v17
	v_add_u32_e32 v226, v16, v18
	v_add_u32_e32 v227, v16, v19
	v_add_u32_e32 v236, v16, v20
	v_mov_b64_e32 v[78:79], v[14:15]
	v_mov_b64_e32 v[62:63], v[14:15]
	v_mov_b64_e32 v[46:47], v[14:15]
	v_mov_b64_e32 v[30:31], v[14:15]
	v_mov_b64_e32 v[94:95], v[14:15]
	v_add_u32_e32 v223, 0x4000, v222
	s_mov_b32 s62, -2
	s_mov_b64 s[50:51], s[20:21]
	v_mov_b64_e32 v[76:77], v[12:13]
	v_mov_b64_e32 v[74:75], v[10:11]
	v_mov_b64_e32 v[72:73], v[8:9]
	v_mov_b64_e32 v[70:71], v[6:7]
	v_mov_b64_e32 v[68:69], v[4:5]
	v_mov_b64_e32 v[66:67], v[2:3]
	v_mov_b64_e32 v[64:65], v[0:1]
	v_mov_b64_e32 v[60:61], v[12:13]
	v_mov_b64_e32 v[58:59], v[10:11]
	v_mov_b64_e32 v[56:57], v[8:9]
	v_mov_b64_e32 v[54:55], v[6:7]
	v_mov_b64_e32 v[52:53], v[4:5]
	v_mov_b64_e32 v[50:51], v[2:3]
	v_mov_b64_e32 v[48:49], v[0:1]
	v_mov_b64_e32 v[44:45], v[12:13]
	v_mov_b64_e32 v[42:43], v[10:11]
	v_mov_b64_e32 v[40:41], v[8:9]
	v_mov_b64_e32 v[38:39], v[6:7]
	v_mov_b64_e32 v[36:37], v[4:5]
	v_mov_b64_e32 v[34:35], v[2:3]
	v_mov_b64_e32 v[32:33], v[0:1]
	v_mov_b64_e32 v[28:29], v[12:13]
	v_mov_b64_e32 v[26:27], v[10:11]
	v_mov_b64_e32 v[24:25], v[8:9]
	v_mov_b64_e32 v[22:23], v[6:7]
	v_mov_b64_e32 v[20:21], v[4:5]
	v_mov_b64_e32 v[18:19], v[2:3]
	v_mov_b64_e32 v[16:17], v[0:1]
	v_mov_b64_e32 v[92:93], v[12:13]
	v_mov_b64_e32 v[90:91], v[10:11]
	v_mov_b64_e32 v[88:89], v[8:9]
	v_mov_b64_e32 v[86:87], v[6:7]
	v_mov_b64_e32 v[84:85], v[4:5]
	v_mov_b64_e32 v[82:83], v[2:3]
	v_mov_b64_e32 v[80:81], v[0:1]
	v_mov_b32_e32 v112, 0
	v_mov_b32_e32 v113, v224
	v_mov_b32_e32 v114, v224
	v_mov_b32_e32 v115, v224
	v_mov_b32_e32 v116, v224
	v_mov_b32_e32 v117, v224
	v_mov_b32_e32 v118, v224
	v_mov_b32_e32 v119, v224
	v_mov_b32_e32 v120, v224
	v_mov_b32_e32 v121, v224
	v_mov_b32_e32 v122, v224
	v_mov_b32_e32 v123, v224
	v_mov_b32_e32 v124, v224
	v_mov_b32_e32 v125, v224
	v_mov_b32_e32 v126, v224
	v_mov_b32_e32 v127, v224
	v_mov_b64_e32 v[176:177], s[8:9]
	v_mov_b64_e32 v[178:179], s[10:11]
	s_waitcnt lgkmcnt(0)
	s_barrier

; #define SBAR() __builtin_amdgcn_sched_barrier(0)
; #define EXP8(P, BASE) do { _Pragma("unroll") for (int r = 0; r < 8; ++r) P[BASE + r] = __builtin_amdgcn_exp2f(P[BASE + r]); } while (0)
; #define LGKM(n) asm volatile("s_waitcnt lgkmcnt(" #n ")" ::: "memory")
; template <int NC> __device__ __forceinline__ void v_mma_k(f32x16* o, f32x16& osum, const s16x4 (&L)[8], bf16x8 pa, bf16x8 ones) {
;     ...
;   osum = __builtin_amdgcn_mfma_f32_32x32x16_bf16(pa, ones, osum, 0, 0, 0);
;   o[0] = __builtin_amdgcn_mfma_f32_32x32x16_bf16(pa, PK(L[0], L[1]), o[0], 0, 0, 0);
;   o[1] = __builtin_amdgcn_mfma_f32_32x32x16_bf16(pa, PK(L[2], L[3]), o[1], 0, 0, 0);
;   if constexpr (NC == 4) { o[2] = __builtin_amdgcn_mfma_f32_32x32x16_bf16(pa, PK(L[4], L[5]), o[2], 0, 0, 0); o[3] = __builtin_amdgcn_mfma_f32_32x32x16_bf16(pa, PK(L[6], L[7]), o[3], 0, 0, 0); }
;     ...
; }
; template <int DV, bool NA>
; __device__ __forceinline__ void attn_core(const bf16_t* __restrict__ Qlane, const bf16_t* __restrict__ Kh, const bf16_t* __restrict__ Vh, const int NT,
;                                           ALAS char* lds, f32x16 (&o)[DV / 32], const NaCtx& na) {
;     ...
;       const int vb = vb0 + b * SHM_V;
;       s16x4 LA[8], LB[8]; bf16x8 pa;
;     ...
;       v_issue_k<NC, 0>(LA, vb);
;       EXP8(p0, 0); PK4(p0, 0, pa); SBAR();
;       v_issue_k<NC, 1>(LB, vb); if constexpr (NC == 4) LGKM(8); else LGKM(4); SBAR(); v_mma_k<NC>(o, osum, LA, pa, ones); SBAR();
;       EXP8(p0, 8); PK4(p0, 8, pa); SBAR();
;       v_issue_k<NC, 2>(LA, vb); if constexpr (NC == 4) LGKM(8); else LGKM(4); SBAR(); v_mma_k<NC>(o, osum, LB, pa, ones); SBAR();
;       EXP8(p1, 0); PK4(p1, 0, pa); SBAR();
;       v_issue_k<NC, 3>(LB, vb); if constexpr (NC == 4) LGKM(8); else LGKM(4); SBAR(); v_mma_k<NC>(o, osum, LA, pa, ones); SBAR();
;       EXP8(p1, 8); PK4(p1, 8, pa); SBAR();
;       LGKM(0); SBAR(); v_mma_k<NC>(o, osum, LB, pa, ones);
.LBB0_276:
	ds_read_b64_tr_b16 v[2:3], v222 offset:0
	ds_read_b64_tr_b16 v[4:5], v222 offset:0x800
	ds_read_b64_tr_b16 v[6:7], v222 offset:0x200
	ds_read_b64_tr_b16 v[8:9], v222 offset:0xa00
	ds_read_b64_tr_b16 v[10:11], v222 offset:0x400
	v_exp_f32_e32 v1, v144
	v_exp_f32_e32 v14, v145
	v_exp_f32_e32 v15, v146
	v_exp_f32_e32 v145, v147
	v_exp_f32_e32 v146, v148
	v_exp_f32_e32 v147, v149
	v_exp_f32_e32 v148, v150
	v_exp_f32_e32 v149, v151
	ds_read_b64_tr_b16 v[12:13], v222 offset:0xc00
	ds_read_b64_tr_b16 v[200:201], v222 offset:0x600
	ds_read_b64_tr_b16 v[202:203], v222 offset:0xe00
	v_cvt_pk_bf16_f32 v144, v1, v14
	v_cvt_pk_bf16_f32 v145, v15, v145
	v_cvt_pk_bf16_f32 v146, v146, v147
	v_cvt_pk_bf16_f32 v147, v148, v149
	s_nop 0
	v_permlane32_swap_b32_e32 v144, v146
	v_permlane32_swap_b32_e32 v145, v147
	s_add_i32 s52, s62, 3
	ds_read_b64_tr_b16 v[148:149], v222 offset:0x1000
	ds_read_b64_tr_b16 v[150:151], v222 offset:0x1800
	ds_read_b64_tr_b16 v[238:239], v222 offset:0x1200
	ds_read_b64_tr_b16 v[240:241], v222 offset:0x1a00
	ds_read_b64_tr_b16 v[242:243], v222 offset:0x1400
	ds_read_b64_tr_b16 v[244:245], v222 offset:0x1c00
	ds_read_b64_tr_b16 v[246:247], v222 offset:0x1600
	ds_read_b64_tr_b16 v[248:249], v222 offset:0x1e00
	s_waitcnt lgkmcnt(8)
	v_mfma_f32_32x32x16_bf16 v[64:79], v[144:147], v[2:5], v[64:79]
	v_mfma_f32_32x32x16_bf16 v[48:63], v[144:147], v[6:9], v[48:63]
	v_mfma_f32_32x32x16_bf16 v[32:47], v[144:147], v[10:13], v[32:47]
	v_mfma_f32_32x32x16_bf16 v[16:31], v[144:147], v[200:203], v[16:31]
	v_exp_f32_e32 v1, v152
	v_exp_f32_e32 v2, v153
	v_exp_f32_e32 v3, v154
	v_exp_f32_e32 v4, v155
	v_exp_f32_e32 v5, v156
	v_exp_f32_e32 v6, v157
	v_exp_f32_e32 v7, v158
	v_exp_f32_e32 v8, v159
	v_cvt_pk_bf16_f32 v2, v1, v2
	v_cvt_pk_bf16_f32 v3, v3, v4
	v_cvt_pk_bf16_f32 v4, v5, v6
	v_cvt_pk_bf16_f32 v5, v7, v8
	s_nop 0
	v_permlane32_swap_b32_e32 v2, v4
	v_permlane32_swap_b32_e32 v3, v5
	ds_read_b64_tr_b16 v[6:7], v222 offset:0x2000
	ds_read_b64_tr_b16 v[8:9], v222 offset:0x2800
	ds_read_b64_tr_b16 v[10:11], v222 offset:0x2200
	ds_read_b64_tr_b16 v[12:13], v222 offset:0x2a00
	ds_read_b64_tr_b16 v[152:153], v222 offset:0x2400
	ds_read_b64_tr_b16 v[154:155], v222 offset:0x2c00
	ds_read_b64_tr_b16 v[156:157], v222 offset:0x2600
	ds_read_b64_tr_b16 v[158:159], v222 offset:0x2e00
	s_waitcnt lgkmcnt(8)
	v_mfma_f32_32x32x16_bf16 v[64:79], v[2:5], v[148:151], v[64:79]
	v_mfma_f32_32x32x16_bf16 v[48:63], v[2:5], v[238:241], v[48:63]
	v_mfma_f32_32x32x16_bf16 v[32:47], v[2:5], v[242:245], v[32:47]
	v_mfma_f32_32x32x16_bf16 v[16:31], v[2:5], v[246:249], v[16:31]
	v_exp_f32_e32 v1, v128
	v_exp_f32_e32 v14, v129
	v_exp_f32_e32 v15, v130
	v_exp_f32_e32 v148, v131
	v_exp_f32_e32 v149, v132
	v_exp_f32_e32 v150, v133
	v_mfma_f32_32x32x16_bf16 v[80:95], v[144:147], v[176:179], v[80:95]
	v_exp_f32_e32 v151, v134
	v_exp_f32_e32 v135, v135
	v_cvt_pk_bf16_f32 v132, v1, v14
	v_cvt_pk_bf16_f32 v133, v15, v148
	v_cvt_pk_bf16_f32 v134, v149, v150
	v_cvt_pk_bf16_f32 v135, v151, v135
	s_nop 0
	v_permlane32_swap_b32_e32 v132, v134
	v_permlane32_swap_b32_e32 v133, v135
	ds_read_b64_tr_b16 v[144:145], v222 offset:0x3000
	ds_read_b64_tr_b16 v[146:147], v222 offset:0x3800
	ds_read_b64_tr_b16 v[148:149], v222 offset:0x3200
	ds_read_b64_tr_b16 v[150:151], v222 offset:0x3a00
	ds_read_b64_tr_b16 v[200:201], v222 offset:0x3400
	ds_read_b64_tr_b16 v[202:203], v222 offset:0x3c00
	ds_read_b64_tr_b16 v[238:239], v222 offset:0x3600
	ds_read_b64_tr_b16 v[240:241], v222 offset:0x3e00
	s_waitcnt lgkmcnt(8)
	v_mfma_f32_32x32x16_bf16 v[64:79], v[132:135], v[6:9], v[64:79]
	v_mfma_f32_32x32x16_bf16 v[48:63], v[132:135], v[10:13], v[48:63]
	v_mfma_f32_32x32x16_bf16 v[32:47], v[132:135], v[152:155], v[32:47]
	v_mfma_f32_32x32x16_bf16 v[16:31], v[132:135], v[156:159], v[16:31]
	v_mfma_f32_32x32x16_bf16 v[80:95], v[2:5], v[176:179], v[80:95]
	v_exp_f32_e32 v1, v136
	v_exp_f32_e32 v6, v137
	v_exp_f32_e32 v7, v138
	v_exp_f32_e32 v8, v139
	v_exp_f32_e32 v9, v140
	v_exp_f32_e32 v4, v141
	v_exp_f32_e32 v5, v142
	v_mfma_f32_32x32x16_bf16 v[80:95], v[132:135], v[176:179], v[80:95]
	v_exp_f32_e32 v10, v143
	v_cvt_pk_bf16_f32 v2, v1, v6
	v_cvt_pk_bf16_f32 v3, v7, v8
	v_cvt_pk_bf16_f32 v4, v9, v4
	v_cvt_pk_bf16_f32 v5, v5, v10
	s_nop 0
	v_permlane32_swap_b32_e32 v2, v4
	v_permlane32_swap_b32_e32 v3, v5
	s_waitcnt lgkmcnt(0)
	s_nop 1
	v_mfma_f32_32x32x16_bf16 v[80:95], v[2:5], v[176:179], v[80:95]
	s_waitcnt lgkmcnt(0)
	s_waitcnt vmcnt(0)
	s_barrier
	s_cmpk_gt_u32 s52, 0xfe
	v_mfma_f32_32x32x16_bf16 v[64:79], v[2:5], v[144:147], v[64:79]
	v_mfma_f32_32x32x16_bf16 v[48:63], v[2:5], v[148:151], v[48:63]
	v_mfma_f32_32x32x16_bf16 v[32:47], v[2:5], v[200:203], v[32:47]
	v_mfma_f32_32x32x16_bf16 v[16:31], v[2:5], v[238:241], v[16:31]
	ds_read_b128 v[156:159], v225 offset:40960
	ds_read_b128 v[200:203], v225 offset:45056
	ds_read_b128 v[152:155], v226 offset:40960
	ds_read_b128 v[148:151], v226 offset:45056
	ds_read_b128 v[144:147], v227 offset:40960
	ds_read_b128 v[10:13], v227 offset:45056
	ds_read_b128 v[2:5], v236 offset:40960
	ds_read_b128 v[6:9], v236 offset:45056
	s_cbranch_scc1 .LBB0_279
	v_lshl_add_u64 v[14:15], s[50:51], 0, v[212:213]
	v_add_co_u32_e32 v14, vcc, 0x1f860400, v14
	v_lshl_add_u64 v[128:129], s[50:51], 0, v[210:211]
	s_add_i32 m0, s98, 0x8000
	v_addc_co_u32_e32 v15, vcc, 0, v15, vcc
	v_add_co_u32_e32 v130, vcc, 0x1f860800, v128
	global_load_lds_dwordx4 v[14:15], off
	s_mov_b32 m0, s98
	v_addc_co_u32_e32 v131, vcc, 0, v129, vcc
	v_add_co_u32_e32 v14, vcc, 0x1f878800, v128
	global_load_lds_dwordx4 v[130:131], off
	s_add_i32 m0, s98, 0x2000
	v_addc_co_u32_e32 v15, vcc, 0, v129, vcc
	global_load_lds_dwordx4 v[14:15], off

; #define SBAR() __builtin_amdgcn_sched_barrier(0)
; #define EXP8(P, BASE) do { _Pragma("unroll") for (int r = 0; r < 8; ++r) P[BASE + r] = __builtin_amdgcn_exp2f(P[BASE + r]); } while (0)
; #define LGKM(n) asm volatile("s_waitcnt lgkmcnt(" #n ")" ::: "memory")
; template <int NC> __device__ __forceinline__ void v_mma_k(f32x16* o, f32x16& osum, const s16x4 (&L)[8], bf16x8 pa, bf16x8 ones) {
;     ...
;   osum = __builtin_amdgcn_mfma_f32_32x32x16_bf16(pa, ones, osum, 0, 0, 0);
;   o[0] = __builtin_amdgcn_mfma_f32_32x32x16_bf16(pa, PK(L[0], L[1]), o[0], 0, 0, 0);
;   o[1] = __builtin_amdgcn_mfma_f32_32x32x16_bf16(pa, PK(L[2], L[3]), o[1], 0, 0, 0);
;   if constexpr (NC == 4) { o[2] = __builtin_amdgcn_mfma_f32_32x32x16_bf16(pa, PK(L[4], L[5]), o[2], 0, 0, 0); o[3] = __builtin_amdgcn_mfma_f32_32x32x16_bf16(pa, PK(L[6], L[7]), o[3], 0, 0, 0); }
;     ...
; }
; template <int DV, bool NA>
; __device__ __forceinline__ void attn_core(const bf16_t* __restrict__ Qlane, const bf16_t* __restrict__ Kh, const bf16_t* __restrict__ Vh, const int NT,
;                                           ALAS char* lds, f32x16 (&o)[DV / 32], const NaCtx& na) {
;     ...
;       const int vb = vb0 + b * SHM_V;
;       s16x4 LA[8], LB[8]; bf16x8 pa;
;     ...
;       v_issue_k<NC, 0>(LA, vb);
;       EXP8(p0, 0); PK4(p0, 0, pa); SBAR();
;       v_issue_k<NC, 1>(LB, vb); if constexpr (NC == 4) LGKM(8); else LGKM(4); SBAR(); v_mma_k<NC>(o, osum, LA, pa, ones); SBAR();
;       EXP8(p0, 8); PK4(p0, 8, pa); SBAR();
;       v_issue_k<NC, 2>(LA, vb); if constexpr (NC == 4) LGKM(8); else LGKM(4); SBAR(); v_mma_k<NC>(o, osum, LB, pa, ones); SBAR();
;       EXP8(p1, 0); PK4(p1, 0, pa); SBAR();
;       v_issue_k<NC, 3>(LB, vb); if constexpr (NC == 4) LGKM(8); else LGKM(4); SBAR(); v_mma_k<NC>(o, osum, LA, pa, ones); SBAR();
;       EXP8(p1, 8); PK4(p1, 8, pa); SBAR();
;       LGKM(0); SBAR(); v_mma_k<NC>(o, osum, LB, pa, ones);
.LBB0_280:
	ds_read_b64_tr_b16 v[2:3], v223 offset:0
	ds_read_b64_tr_b16 v[4:5], v223 offset:0x800
	ds_read_b64_tr_b16 v[6:7], v223 offset:0x200
	ds_read_b64_tr_b16 v[8:9], v223 offset:0xa00
	ds_read_b64_tr_b16 v[10:11], v223 offset:0x400
	ds_read_b64_tr_b16 v[12:13], v223 offset:0xc00
	v_exp_f32_e32 v1, v128
	v_exp_f32_e32 v14, v129
	v_exp_f32_e32 v15, v130
	v_exp_f32_e32 v129, v131
	v_exp_f32_e32 v130, v132
	v_exp_f32_e32 v131, v133
	v_exp_f32_e32 v132, v134
	v_exp_f32_e32 v133, v135
	ds_read_b64_tr_b16 v[144:145], v223 offset:0x600
	ds_read_b64_tr_b16 v[146:147], v223 offset:0xe00
	v_cvt_pk_bf16_f32 v128, v1, v14
	v_cvt_pk_bf16_f32 v129, v15, v129
	v_cvt_pk_bf16_f32 v130, v130, v131
	v_cvt_pk_bf16_f32 v131, v132, v133
	s_nop 0
	v_permlane32_swap_b32_e32 v128, v130
	v_permlane32_swap_b32_e32 v129, v131
	ds_read_b64_tr_b16 v[132:133], v223 offset:0x1000
	ds_read_b64_tr_b16 v[134:135], v223 offset:0x1800
	ds_read_b64_tr_b16 v[148:149], v223 offset:0x1200
	ds_read_b64_tr_b16 v[150:151], v223 offset:0x1a00
	ds_read_b64_tr_b16 v[152:153], v223 offset:0x1400
	ds_read_b64_tr_b16 v[154:155], v223 offset:0x1c00
	ds_read_b64_tr_b16 v[156:157], v223 offset:0x1600
	ds_read_b64_tr_b16 v[158:159], v223 offset:0x1e00
	s_waitcnt lgkmcnt(8)
	v_mfma_f32_32x32x16_bf16 v[64:79], v[128:131], v[2:5], v[64:79]
	v_mfma_f32_32x32x16_bf16 v[48:63], v[128:131], v[6:9], v[48:63]
	v_mfma_f32_32x32x16_bf16 v[32:47], v[128:131], v[10:13], v[32:47]
	v_mfma_f32_32x32x16_bf16 v[16:31], v[128:131], v[144:147], v[16:31]
	v_exp_f32_e32 v1, v136
	v_exp_f32_e32 v2, v137
	v_exp_f32_e32 v3, v138
	v_exp_f32_e32 v4, v139
	v_exp_f32_e32 v5, v140
	v_exp_f32_e32 v6, v141
	v_exp_f32_e32 v7, v142
	v_exp_f32_e32 v8, v143
	v_cvt_pk_bf16_f32 v2, v1, v2
	v_cvt_pk_bf16_f32 v3, v3, v4
	v_cvt_pk_bf16_f32 v4, v5, v6
	v_cvt_pk_bf16_f32 v5, v7, v8
	s_nop 0
	v_permlane32_swap_b32_e32 v2, v4
	v_permlane32_swap_b32_e32 v3, v5
	ds_read_b64_tr_b16 v[6:7], v223 offset:0x2000
	ds_read_b64_tr_b16 v[8:9], v223 offset:0x2800
	ds_read_b64_tr_b16 v[10:11], v223 offset:0x2200
	ds_read_b64_tr_b16 v[12:13], v223 offset:0x2a00
	ds_read_b64_tr_b16 v[136:137], v223 offset:0x2400
	ds_read_b64_tr_b16 v[138:139], v223 offset:0x2c00
	ds_read_b64_tr_b16 v[140:141], v223 offset:0x2600
	ds_read_b64_tr_b16 v[142:143], v223 offset:0x2e00
	s_waitcnt lgkmcnt(8)
	v_mfma_f32_32x32x16_bf16 v[64:79], v[2:5], v[132:135], v[64:79]
	v_mfma_f32_32x32x16_bf16 v[48:63], v[2:5], v[148:151], v[48:63]
	v_mfma_f32_32x32x16_bf16 v[32:47], v[2:5], v[152:155], v[32:47]
	v_mfma_f32_32x32x16_bf16 v[16:31], v[2:5], v[156:159], v[16:31]
	v_exp_f32_e32 v1, v96
	v_exp_f32_e32 v14, v97
	v_exp_f32_e32 v15, v98
	v_exp_f32_e32 v132, v99
	v_exp_f32_e32 v133, v100
	v_exp_f32_e32 v134, v101
	v_mfma_f32_32x32x16_bf16 v[80:95], v[128:131], v[176:179], v[80:95]
	v_exp_f32_e32 v135, v102
	v_exp_f32_e32 v103, v103
	v_cvt_pk_bf16_f32 v100, v1, v14
	v_cvt_pk_bf16_f32 v101, v15, v132
	v_cvt_pk_bf16_f32 v102, v133, v134
	v_cvt_pk_bf16_f32 v103, v135, v103
	s_nop 0
	v_permlane32_swap_b32_e32 v100, v102
	v_permlane32_swap_b32_e32 v101, v103
	ds_read_b64_tr_b16 v[128:129], v223 offset:0x3000
	ds_read_b64_tr_b16 v[130:131], v223 offset:0x3800
	ds_read_b64_tr_b16 v[132:133], v223 offset:0x3200
	ds_read_b64_tr_b16 v[134:135], v223 offset:0x3a00
	ds_read_b64_tr_b16 v[144:145], v223 offset:0x3400
	ds_read_b64_tr_b16 v[146:147], v223 offset:0x3c00
	ds_read_b64_tr_b16 v[148:149], v223 offset:0x3600
	ds_read_b64_tr_b16 v[150:151], v223 offset:0x3e00
	s_waitcnt lgkmcnt(8)
	v_mfma_f32_32x32x16_bf16 v[64:79], v[100:103], v[6:9], v[64:79]
	v_mfma_f32_32x32x16_bf16 v[48:63], v[100:103], v[10:13], v[48:63]
	v_mfma_f32_32x32x16_bf16 v[32:47], v[100:103], v[136:139], v[32:47]
	v_mfma_f32_32x32x16_bf16 v[16:31], v[100:103], v[140:143], v[16:31]
	v_mfma_f32_32x32x16_bf16 v[80:95], v[2:5], v[176:179], v[80:95]
	v_exp_f32_e32 v1, v104
	v_exp_f32_e32 v6, v105
	v_exp_f32_e32 v7, v106
	v_exp_f32_e32 v8, v107
	v_exp_f32_e32 v9, v108
	v_exp_f32_e32 v4, v109
	v_exp_f32_e32 v5, v110
	v_mfma_f32_32x32x16_bf16 v[80:95], v[100:103], v[176:179], v[80:95]
	v_exp_f32_e32 v10, v111
	v_cvt_pk_bf16_f32 v2, v1, v6
	v_cvt_pk_bf16_f32 v3, v7, v8
	v_cvt_pk_bf16_f32 v4, v9, v4
	v_cvt_pk_bf16_f32 v5, v5, v10
	s_nop 0
	v_permlane32_swap_b32_e32 v2, v4
	v_permlane32_swap_b32_e32 v3, v5
	s_waitcnt lgkmcnt(0)
	s_nop 1
	v_mfma_f32_32x32x16_bf16 v[80:95], v[2:5], v[176:179], v[80:95]
	s_add_u32 s50, s50, 0x60000
	s_addc_u32 s51, s51, 0
	s_cmpk_lt_u32 s61, 0xfe
	s_waitcnt vmcnt(0)
	s_barrier
	v_mfma_f32_32x32x16_bf16 v[64:79], v[2:5], v[128:131], v[64:79]
	v_mfma_f32_32x32x16_bf16 v[48:63], v[2:5], v[132:135], v[48:63]
	v_mfma_f32_32x32x16_bf16 v[32:47], v[2:5], v[144:147], v[32:47]
	v_mfma_f32_32x32x16_bf16 v[16:31], v[2:5], v[148:151], v[16:31]
	s_cbranch_scc0 .LBB0_288
	s_mov_b32 s62, s61
	s_branch .LBB0_272
